# v15 + first K/V tile-pair loads of each attention item issued right after the Q loads, before the block gate
# speedup vs baseline: 1.0018x; 1.0018x over previous
; __device__ __forceinline__ void phase_attn(const Params& p, LAS unsigned char* lds, unsigned* queue) {
;     ...
;         const int idx = (int)*tick;
;         if (idx >= 512) break;
;         const int blk = 7 - (idx >> 6), bh = idx & 63, b = bh >> 3, h = bh & 7;
;         const int qpos = blk * 256 + w * 32 + r;
;         const bf16_t* Qp = Qg + ((size_t)bh * 2048 + qpos) * 64 + 8 * hh;
;         bf16x8 qf[4];
; #pragma unroll
;         for (int s = 0; s < 4; ++s) qf[s] = *(const bf16x8*)(Qp + 16 * s);
;         unsigned selmask;
;         if (blk <= 3) selmask = (1u << blk) - 1u;
;         else {
;             float v1 = -3e38f, v2 = -3e38f, v3 = -3e38f; int i1 = 0, i2 = 0, i3 = 0;
;     ...
;         const bf16_t* Kst = Kg + ((size_t)bh * 2048 + srow) * 64 + sch * 8;
;         const bf16_t* Vst = VTg + ((size_t)bh * 64 + srow) * 2048 + sch * 8;
;         u32x4 kreg[2], vreg[2];
; #pragma unroll
;         for (int q = 0; q < 2; ++q) { const int kp = blk * 256 + 64 * q; kreg[q] = *(const u32x4*)(Kst + (size_t)kp * 64); vreg[q] = *(const u32x4*)(Vst + kp); }
.LBB0_337:
	s_or_b64 exec, exec, s[4:5]
	s_waitcnt lgkmcnt(0)
	s_barrier
	ds_read_b32 v2, v212
	s_movk_i32 s0, 0x1ff
	s_mov_b64 s[4:5], -1
	s_waitcnt lgkmcnt(0)
	v_cmp_lt_i32_e32 vcc, s0, v2
	v_readfirstlane_b32 s96, v2
	s_cbranch_vccnz .LBB0_332
	s_ashr_i32 s1, s96, 6
	s_sub_i32 s0, 7, s1
	s_and_b32 s97, s96, 63
	s_lshl_b32 s4, s0, 8
	v_add_u32_e32 v187, s4, v199
	s_lshl_b32 s82, s97, 11
	v_add_u32_e32 v2, s82, v187
	v_lshlrev_b64 v[4:5], 7, v[2:3]
	v_lshl_add_u64 v[4:5], v[178:179], 0, v[4:5]
	global_load_dwordx4 v[146:149], v[4:5], off
	global_load_dwordx4 v[150:153], v[4:5], off offset:32
	global_load_dwordx4 v[154:157], v[4:5], off offset:64
	global_load_dwordx4 v[158:161], v[4:5], off offset:96
	v_or_b32_e32 v2, s82, v200
	v_lshlrev_b32_e32 v2, 7, v2
	s_lshl_b32 s98, s97, 18
	s_mov_b32 s99, 0
	v_lshl_add_u64 v[188:189], v[182:183], 0, v[2:3]
	v_lshl_add_u64 v[190:191], v[184:185], 0, s[98:99]
	s_mov_b32 s100, s4
	s_mov_b32 s101, 0
	s_lshl_b64 s[98:99], s[100:101], 7
	v_lshl_add_u64 v[4:5], v[188:189], 0, s[98:99]
	s_or_b32 s98, s4, 64
	s_mov_b32 s99, 0
	s_lshl_b64 s[98:99], s[98:99], 7
	v_lshl_add_u64 v[6:7], s[100:101], 1, v[190:191]
	global_load_dwordx4 v[162:165], v[4:5], off
	global_load_dwordx4 v[166:169], v[6:7], off
	v_lshl_add_u64 v[4:5], v[188:189], 0, s[98:99]
	global_load_dwordx4 v[170:173], v[4:5], off
	global_load_dwordx4 v[174:177], v[6:7], off offset:128
	s_cmp_gt_i32 s1, 3
	s_mov_b64 s[6:7], -1
	s_cbranch_scc1 .LBB0_380
; __device__ __forceinline__ float bf2f(unsigned short b) { return __uint_as_float(((unsigned)b) << 16); }
; __device__ __forceinline__ void phase_attn(const Params& p, LAS unsigned char* lds, unsigned* queue) {
;     ...
;             float v1 = -3e38f, v2 = -3e38f, v3 = -3e38f; int i1 = 0, i2 = 0, i3 = 0;
; #pragma unroll
;             for (int j = 0; j < 7; ++j) {
;                 if (j < blk) {
;                     const float* ks = KSUM + ((size_t)bh * 8 + j) * 64 + 8 * hh;
;                     float gsum = 0.f;
; #pragma unroll
;                     for (int s = 0; s < 4; ++s) {
;                         const f32x4 k0 = *(const f32x4*)(ks + 16 * s), k1 = *(const f32x4*)(ks + 16 * s + 4);
;                         gsum += bf2f((unsigned short)qf[s][0]) * k0[0] + bf2f((unsigned short)qf[s][1]) * k0[1] + bf2f((unsigned short)qf[s][2]) * k0[2] + bf2f((unsigned short)qf[s][3]) * k0[3]
;                               + bf2f((unsigned short)qf[s][4]) * k1[0] + bf2f((unsigned short)qf[s][5]) * k1[1] + bf2f((unsigned short)qf[s][6]) * k1[2] + bf2f((unsigned short)qf[s][7]) * k1[3];
;                     }
;                     gsum += __shfl_xor(gsum, 32);
;                     if (gsum > v1) { v3 = v2; i3 = i2; v2 = v1; i2 = i1; v1 = gsum; i1 = j; }
;                     else if (gsum > v2) { v3 = v2; i3 = i2; v2 = gsum; i2 = j; }
;                     else if (gsum > v3) { v3 = gsum; i3 = j; }
	v_lshl_add_u64 v[12:13], v[180:181], 0, s[82:83]
	global_load_dwordx4 v[30:33], v[12:13], off
	global_load_dwordx4 v[8:11], v[12:13], off offset:64
	global_load_dwordx4 v[34:37], v[12:13], off offset:16
	global_load_dwordx4 v[4:7], v[12:13], off offset:80
	global_load_dwordx4 v[38:41], v[12:13], off offset:128
	global_load_dwordx4 v[42:45], v[12:13], off offset:192
	global_load_dwordx4 v[46:49], v[12:13], off offset:144
	global_load_dwordx4 v[50:53], v[12:13], off offset:208
	global_load_dwordx4 v[54:57], v[12:13], off offset:272
	global_load_dwordx4 v[58:61], v[12:13], off offset:256
	global_load_dwordx4 v[62:65], v[12:13], off offset:336
	global_load_dwordx4 v[66:69], v[12:13], off offset:320
	s_waitcnt vmcnt(14)
	v_and_b32_e32 v19, 0xffff0000, v150
	v_and_b32_e32 v18, 0xffff0000, v146
	v_lshlrev_b32_e32 v15, 16, v150
	v_lshlrev_b32_e32 v14, 16, v146
	v_lshlrev_b32_e32 v17, 16, v151
	v_lshlrev_b32_e32 v16, 16, v147
	v_and_b32_e32 v29, 0xffff0000, v151
	v_and_b32_e32 v28, 0xffff0000, v147
	v_lshlrev_b32_e32 v27, 16, v152
	v_lshlrev_b32_e32 v26, 16, v148
	v_and_b32_e32 v25, 0xffff0000, v152
	v_and_b32_e32 v24, 0xffff0000, v148
	v_lshlrev_b32_e32 v23, 16, v153
	v_lshlrev_b32_e32 v22, 16, v149
	v_and_b32_e32 v21, 0xffff0000, v153
	v_and_b32_e32 v20, 0xffff0000, v149
	v_cmp_lt_i32_e32 vcc, v193, v202
	s_waitcnt vmcnt(11)
	v_mov_b32_e32 v70, v30
	s_waitcnt vmcnt(10)
	v_mov_b32_e32 v71, v8
	v_mov_b32_e32 v8, v31
	v_pk_mul_f32 v[8:9], v[8:9], v[18:19]
	v_mov_b32_e32 v72, v32
	v_mov_b32_e32 v73, v10
	v_pk_fma_f32 v[8:9], v[70:71], v[14:15], v[8:9]
	v_mov_b32_e32 v10, v33
	s_waitcnt vmcnt(9)
	v_mov_b32_e32 v74, v34
	s_waitcnt vmcnt(8)
	v_mov_b32_e32 v75, v4
	v_mov_b32_e32 v4, v35
	s_waitcnt vmcnt(7)
	v_mov_b32_e32 v34, v38
	s_waitcnt vmcnt(6)
	v_mov_b32_e32 v35, v42
	v_mov_b32_e32 v42, v39
	v_and_b32_e32 v33, 0xffff0000, v158
	v_and_b32_e32 v32, 0xffff0000, v154
	v_pk_fma_f32 v[38:39], v[72:73], v[16:17], v[8:9]
	v_mov_b32_e32 v76, v36
	v_mov_b32_e32 v77, v6
	v_mov_b32_e32 v6, v37
	v_mov_b32_e32 v36, v40
	v_mov_b32_e32 v37, v44
	v_mov_b32_e32 v44, v41
	v_lshlrev_b32_e32 v31, 16, v158
	v_lshlrev_b32_e32 v30, 16, v154
	v_pk_fma_f32 v[38:39], v[10:11], v[28:29], v[38:39]
	v_pk_mul_f32 v[40:41], v[42:43], v[32:33]
	v_lshlrev_b32_e32 v9, 16, v159
	v_lshlrev_b32_e32 v8, 16, v155
	v_pk_fma_f32 v[40:41], v[34:35], v[30:31], v[40:41]
	v_pk_fma_f32 v[38:39], v[74:75], v[26:27], v[38:39]
	v_and_b32_e32 v11, 0xffff0000, v159
	v_and_b32_e32 v10, 0xffff0000, v155
	v_pk_fma_f32 v[40:41], v[36:37], v[8:9], v[40:41]
	v_pk_fma_f32 v[4:5], v[4:5], v[24:25], v[38:39]
	s_waitcnt vmcnt(5)
	v_mov_b32_e32 v78, v46
	s_waitcnt vmcnt(4)
	v_mov_b32_e32 v79, v50
	v_mov_b32_e32 v50, v47
	v_mov_b32_e32 v80, v48
	v_mov_b32_e32 v81, v52
	v_mov_b32_e32 v52, v49
	v_lshlrev_b32_e32 v35, 16, v160
	v_lshlrev_b32_e32 v34, 16, v156
	v_pk_fma_f32 v[70:71], v[44:45], v[10:11], v[40:41]
	v_pk_fma_f32 v[4:5], v[76:77], v[22:23], v[4:5]
	global_load_dwordx4 v[38:41], v[12:13], off offset:400
	global_load_dwordx4 v[42:45], v[12:13], off offset:384
	global_load_dwordx4 v[46:49], v[12:13], off offset:448
	v_and_b32_e32 v37, 0xffff0000, v160
	v_pk_fma_f32 v[72:73], v[6:7], v[20:21], v[4:5]
	v_and_b32_e32 v36, 0xffff0000, v156
	v_pk_fma_f32 v[6:7], v[78:79], v[34:35], v[70:71]
	v_lshlrev_b32_e32 v5, 16, v161
	v_lshlrev_b32_e32 v4, 16, v157
	v_pk_fma_f32 v[6:7], v[50:51], v[36:37], v[6:7]
	v_add_f32_e32 v2, 0, v72
	v_pk_fma_f32 v[50:51], v[80:81], v[4:5], v[6:7]
	v_and_b32_e32 v7, 0xffff0000, v161
	v_and_b32_e32 v6, 0xffff0000, v157
	v_pk_fma_f32 v[70:71], v[52:53], v[6:7], v[50:51]
	global_load_dwordx4 v[50:53], v[12:13], off offset:464
	v_add_f32_e32 v2, v2, v73
	s_waitcnt vmcnt(4)
	v_mov_b32_e32 v73, v66
	v_mov_b32_e32 v66, v59
	v_mov_b32_e32 v72, v58
	v_pk_mul_f32 v[58:59], v[66:67], v[18:19]
	v_mov_b32_e32 v66, v60
	v_pk_fma_f32 v[58:59], v[72:73], v[14:15], v[58:59]
	v_mov_b32_e32 v67, v68
	v_pk_fma_f32 v[58:59], v[66:67], v[16:17], v[58:59]
	v_mov_b32_e32 v68, v61
	v_pk_fma_f32 v[58:59], v[68:69], v[28:29], v[58:59]
	v_mov_b32_e32 v60, v54
	v_mov_b32_e32 v61, v62
	v_pk_fma_f32 v[58:59], v[60:61], v[26:27], v[58:59]
	v_mov_b32_e32 v62, v55
	v_pk_fma_f32 v[54:55], v[62:63], v[24:25], v[58:59]
	v_mov_b32_e32 v58, v56
	v_mov_b32_e32 v59, v64
	v_pk_fma_f32 v[54:55], v[58:59], v[22:23], v[54:55]
	v_mov_b32_e32 v64, v57
	v_pk_fma_f32 v[54:55], v[64:65], v[20:21], v[54:55]
	v_add_f32_e32 v2, v2, v70
	v_add_f32_e32 v54, 0, v54
	v_add_f32_e32 v56, v54, v55
	v_add_f32_e32 v70, v2, v71
	v_cndmask_b32_e32 v2, v192, v193, vcc
	v_lshlrev_b32_e32 v2, 2, v2
	ds_bpermute_b32 v66, v2, v70
	s_waitcnt vmcnt(2)
	v_mov_b32_e32 v54, v42
	s_waitcnt vmcnt(1)
	v_mov_b32_e32 v55, v46
	v_mov_b32_e32 v46, v43
	v_pk_mul_f32 v[42:43], v[46:47], v[32:33]
	v_mov_b32_e32 v46, v44
	v_pk_fma_f32 v[42:43], v[54:55], v[30:31], v[42:43]
	v_mov_b32_e32 v47, v48
	v_pk_fma_f32 v[42:43], v[46:47], v[8:9], v[42:43]
	v_mov_b32_e32 v48, v45
	v_pk_fma_f32 v[42:43], v[48:49], v[10:11], v[42:43]
	v_mov_b32_e32 v44, v38
	s_waitcnt vmcnt(0)
	v_mov_b32_e32 v45, v50
	v_pk_fma_f32 v[42:43], v[44:45], v[34:35], v[42:43]
	v_mov_b32_e32 v50, v39
	v_pk_fma_f32 v[38:39], v[50:51], v[36:37], v[42:43]
	v_mov_b32_e32 v42, v40
	v_mov_b32_e32 v43, v52
	v_pk_fma_f32 v[38:39], v[42:43], v[4:5], v[38:39]
	v_mov_b32_e32 v52, v41
	v_pk_fma_f32 v[38:39], v[52:53], v[6:7], v[38:39]
	v_mov_b32_e32 v44, 0
	v_add_f32_e32 v38, v56, v38
	v_add_f32_e32 v39, v38, v39
	ds_bpermute_b32 v40, v2, v39
	s_waitcnt lgkmcnt(1)
	v_add_f32_e32 v38, v70, v66
	v_max_f32_e32 v38, 0xff61b1e6, v38
	v_mov_b32_e32 v41, 1
	v_mov_b32_e32 v45, v38
	s_waitcnt lgkmcnt(0)
	v_add_f32_e32 v40, v39, v40
	v_cmp_ngt_f32_e32 vcc, v40, v38
	s_and_saveexec_b64 s[6:7], vcc
	s_cbranch_execz .LBB0_343
	s_mov_b32 s5, 0xff61b1e6
	v_cmp_nlt_f32_e32 vcc, s5, v40
	v_mov_b32_e32 v44, 1
	s_and_saveexec_b64 s[8:9], vcc
	v_mov_b32_e32 v44, 0
	v_mov_b32_e32 v40, 0xff61b1e6
	s_or_b64 exec, exec, s[8:9]
	v_mov_b32_e32 v41, 0
	v_mov_b32_e32 v45, v40
	v_mov_b32_e32 v40, v38

; #define LAS __attribute__((address_space(3)))
; template <bool DIAG>
; __device__ __forceinline__ void attn_tile(LAS unsigned char* B, unsigned kf_off, unsigned vf_off, const bf16x8 (&qf)[4], f32x16& O0, f32x16& O1, float& mrun, float& lrun,
;                                           bool on, int kpos0, int qpos, int hh) {
;     ...
;         for (int i = 0; i < 16; ++i) {
;             const int key = kpos0 + (i & 7) + 8 * hh + 16 * (i >> 3);
;             if (key > qpos) st0[i] = -1e30f;
;             if (key + 32 > qpos) st1[i] = -1e30f;
; __device__ __forceinline__ void phase_attn(const Params& p, LAS unsigned char* lds, unsigned* queue) {
;     ...
;         const int ntile = 4 + 4 * blk;
;         const bf16_t* Kst = Kg + ((size_t)bh * 2048 + srow) * 64 + sch * 8;
;         const bf16_t* Vst = VTg + ((size_t)bh * 64 + srow) * 2048 + sch * 8;
;         u32x4 kreg[2], vreg[2];
; #pragma unroll
;         for (int q = 0; q < 2; ++q) { const int kp = blk * 256 + 64 * q; kreg[q] = *(const u32x4*)(Kst + (size_t)kp * 64); vreg[q] = *(const u32x4*)(Vst + kp); }
; #pragma unroll
;         for (int q = 0; q < 2; ++q) { *(LAS u32x4*)(lds + q * BUFB + st_off) = kreg[q]; *(LAS u32x4*)(lds + q * BUFB + TILEB + st_off) = vreg[q]; }
;         __syncthreads();
.LBB0_382:
	v_or_b32_e32 v2, s82, v200
	v_lshlrev_b32_e32 v2, 7, v2
	s_lshl_b32 s82, s97, 18
	s_mov_b32 s5, s83
	v_lshl_add_u64 v[188:189], v[182:183], 0, v[2:3]
	v_lshl_add_u64 v[190:191], v[184:185], 0, s[82:83]
	s_lshl_b64 s[6:7], s[4:5], 7
	s_or_b32 s82, s4, 64
	v_lshl_add_u64 v[4:5], v[188:189], 0, s[6:7]
	s_lshl_b64 s[6:7], s[82:83], 7
	v_lshl_add_u64 v[6:7], s[4:5], 1, v[190:191]
	v_lshl_add_u64 v[4:5], v[188:189], 0, s[6:7]
	v_or_b32_e32 v2, s4, v203
	v_add_u32_e32 v2, s88, v2
	v_or_b32_e32 v4, 32, v2
	v_or_b32_e32 v16, 7, v2
	v_or_b32_e32 v17, 39, v2
	v_cmp_gt_i32_e64 s[8:9], v4, v187
	v_or_b32_e32 v4, 54, v2
	s_or_b32 s94, s4, 0x80
	s_or_b32 s95, s4, 0xc0
	v_cmp_gt_i32_e64 s[4:5], v2, v187
	v_cmp_lt_i32_e64 s[6:7], v2, v187
	v_or_b32_e32 v5, 33, v2
	v_or_b32_e32 v6, 2, v2
	v_or_b32_e32 v7, 34, v2
	v_or_b32_e32 v8, 3, v2
	v_or_b32_e32 v9, 35, v2
	v_or_b32_e32 v10, 4, v2
	v_or_b32_e32 v11, 36, v2
	v_or_b32_e32 v12, 5, v2
	v_or_b32_e32 v13, 37, v2
	v_or_b32_e32 v14, 6, v2
	v_or_b32_e32 v15, 38, v2
	v_or_b32_e32 v18, 16, v2
	v_or_b32_e32 v19, 48, v2
	v_or_b32_e32 v20, 17, v2
	v_or_b32_e32 v21, 49, v2
	v_or_b32_e32 v22, 18, v2
	v_or_b32_e32 v23, 50, v2
	v_or_b32_e32 v24, 19, v2
	v_or_b32_e32 v25, 51, v2
	v_or_b32_e32 v26, 20, v2
	v_or_b32_e32 v27, 52, v2
	v_or_b32_e32 v28, 21, v2
	v_or_b32_e32 v29, 53, v2
	v_or_b32_e32 v30, 22, v2
	v_cmp_gt_i32_e64 s[34:35], v16, v187
	v_cmp_gt_i32_e64 s[36:37], v17, v187
	v_cmp_gt_i32_e64 s[64:65], v4, v187
	v_or_b32_e32 v4, 23, v2
	v_or_b32_e32 v2, 55, v2
	v_mov_b32_e32 v16, v3
	v_mov_b32_e32 v17, v3
	s_lshl_b32 s33, s0, 2
	v_cmp_gt_i32_e64 s[10:11], v5, v187
	v_cmp_gt_i32_e64 s[12:13], v6, v187
	v_cmp_gt_i32_e64 s[14:15], v7, v187
	v_cmp_gt_i32_e64 s[16:17], v8, v187
	v_cmp_gt_i32_e64 s[18:19], v9, v187
	v_cmp_gt_i32_e64 s[20:21], v10, v187
	v_cmp_gt_i32_e64 s[22:23], v11, v187
	v_cmp_gt_i32_e64 s[24:25], v12, v187
	v_cmp_gt_i32_e64 s[26:27], v13, v187
	v_cmp_gt_i32_e64 s[28:29], v14, v187
	v_cmp_gt_i32_e64 s[30:31], v15, v187
	v_cmp_gt_i32_e64 s[38:39], v18, v187
	v_cmp_gt_i32_e64 s[40:41], v19, v187
	v_cmp_gt_i32_e64 s[42:43], v20, v187
	v_cmp_gt_i32_e64 s[44:45], v21, v187
	v_cmp_gt_i32_e64 s[46:47], v22, v187
	v_cmp_gt_i32_e64 s[48:49], v23, v187
	v_cmp_gt_i32_e64 s[50:51], v24, v187
	v_cmp_gt_i32_e64 s[52:53], v25, v187
	v_cmp_gt_i32_e64 s[54:55], v26, v187
	v_cmp_gt_i32_e64 s[56:57], v27, v187
	v_cmp_gt_i32_e64 s[58:59], v28, v187
	v_cmp_gt_i32_e64 s[60:61], v29, v187
	v_cmp_gt_i32_e64 s[62:63], v30, v187
	v_cmp_gt_i32_e64 s[66:67], v4, v187
	v_cmp_gt_i32_e64 s[68:69], v2, v187
	v_mov_b32_e32 v2, v3
	v_mov_b32_e32 v4, v3
	v_mov_b32_e32 v5, v3
	v_mov_b32_e32 v6, v3
	v_mov_b32_e32 v7, v3
	v_mov_b32_e32 v8, v3
	v_mov_b32_e32 v9, v3
	v_mov_b32_e32 v10, v3
	v_mov_b32_e32 v11, v3
	v_mov_b32_e32 v12, v3
	v_mov_b32_e32 v13, v3
	v_mov_b32_e32 v14, v3
	v_mov_b32_e32 v15, v3
	v_mov_b64_e32 v[32:33], v[16:17]
	v_mov_b64_e32 v[48:49], v[16:17]
	s_add_i32 s33, s33, 4
	s_mov_b32 s78, 0
	v_mov_b32_e32 v214, 0
	s_mov_b32 s79, 0x7fffff80
	s_mov_b32 s0, 0
	v_mov_b64_e32 v[30:31], v[14:15]
	v_mov_b64_e32 v[28:29], v[12:13]
	v_mov_b64_e32 v[26:27], v[10:11]
	v_mov_b64_e32 v[24:25], v[8:9]
	v_mov_b64_e32 v[22:23], v[6:7]
	v_mov_b64_e32 v[20:21], v[4:5]
	v_mov_b64_e32 v[18:19], v[2:3]
	v_mov_b64_e32 v[46:47], v[14:15]
	v_mov_b64_e32 v[44:45], v[12:13]
	v_mov_b64_e32 v[42:43], v[10:11]
	v_mov_b64_e32 v[40:41], v[8:9]
	v_mov_b64_e32 v[38:39], v[6:7]
	v_mov_b64_e32 v[36:37], v[4:5]
	v_mov_b64_e32 v[34:35], v[2:3]
	v_mov_b32_e32 v2, 0
	s_waitcnt vmcnt(3)
	ds_write_b128 v204, v[162:165]
	s_waitcnt vmcnt(2)
	ds_write_b128 v204, v[166:169] offset:9216
	s_waitcnt vmcnt(1)
	ds_write_b128 v204, v[170:173] offset:18432
	s_waitcnt vmcnt(0)
	ds_write_b128 v204, v[174:177] offset:27648
	s_waitcnt lgkmcnt(0)
	s_barrier
